# y1 + dilated attention: previous-group row and LSE loads as global_load instead of flat_load (no lgkmcnt pollution of the LDS waits)
# baseline (speedup 1.0000x reference)
; template <int MODE> ...
;     ...
;             for (int i = tid; i < 2 * 129; i += NT_) { const int mm = i / 129, ii = i - mm * 129; biasL[mm * 2048 + ii] = biasT[(size_t)(2 * hp + mm) * 2048 + min(ii * dil, 2047)]; }
;         }
;     }
;     const int q_lo = 128 * jblk + 32 * wq;
;     const int qi = q_lo + r32;
;     const size_t qtok = tok0 + (size_t)qi * dil;
;     bf16x8 qf[4];
; #pragma unroll
;     for (int ds = 0; ds < 4; ++ds) qf[ds] = *(const GAS bf16x8*)(QK + qtok * 2048 + (2 * hp + mp) * 64 + 16 * ds + 8 * hi);
;     const int kt_hi = 2 * jblk + 1;
;     const int kt_lo = (MODE == 0) ? 0 : ((jblk > 0) ? 2 * jblk - 2 : 0);
;     const int kp_row0 = tid >> 4, kp_c = tid & 15;
;     const int vp_row0 = tid >> 3, vp_c = tid & 7;
;     const bf16* ksrc = QK + 1024 + 2 * hp * 64 + kp_c * 8;
;     const bf16* vsrc = Vt + (size_t)(2 * hp * 64 + vp_row0) * TOK + vcol0 + vp_c * 8;
;     u32x4 kr0, kr1, vr0, vr1;
;     {
;         const int kv0 = 64 * kt_lo;
;         kr0 = *(const GAS u32x4*)(ksrc + (tok0 + (size_t)(kv0 + kp_row0) * dil) * 2048);
;         kr1 = *(const GAS u32x4*)(ksrc + (tok0 + (size_t)(kv0 + kp_row0 + 32) * dil) * 2048);
;         vr0 = *(const GAS u32x4*)(vsrc + kv0);
;         vr1 = *(const GAS u32x4*)(vsrc + (size_t)64 * TOK + kv0);
;         LAS unsigned char* kb = lds; LAS unsigned char* vb = lds + AT_KBYTES;
;         *(LAS u32x4*)(kb + kp_row0 * AT_KROW + kp_c * 16) = kr0; *(LAS u32x4*)(kb + (kp_row0 + 32) * AT_KROW + kp_c * 16) = kr1;
;         { LAS unsigned char* p0 = vb + vp_row0 * AT_VROW + vp_c * 16; LAS unsigned char* p1 = vb + (vp_row0 + 64) * AT_VROW + vp_c * 16;
;           *(LAS u32x2*)p0 = (u32x2){vr0.x, vr0.y}; *(LAS u32x2*)(p0 + 8) = (u32x2){vr0.z, vr0.w}; *(LAS u32x2*)p1 = (u32x2){vr1.x, vr1.y}; *(LAS u32x2*)(p1 + 8) = (u32x2){vr1.z, vr1.w}; }
;     }
;     f32x16 acc[NDV];
; #pragma unroll
;     for (int i = 0; i < NDV; ++i)
; #pragma unroll
;         for (int r = 0; r < 16; ++r) acc[i][r] = 0.f;
;     float mrun = -1e30f, lsum = 0.f;
;     float la_pre = 0.f; u32x2 pw_pre[NDV][4];
;     if (MODE == 1 && gidx > 0) {
;         la_pre = LSE[qtok * 16 + 2 * hp + mp];
; #pragma unroll
;         for (int dvb = 0; dvb < NDV; ++dvb)
; #pragma unroll
;             for (int g4 = 0; g4 < 4; ++g4) pw_pre[dvb][g4] = *(const u32x2*)(AO + qtok * 1024 + (2 * hp + mp) * 64 + 32 * dvb + 8 * g4 + 4 * hi);
.LBB0_429:
	s_mov_b32 s12, 0xfe03f81
	v_mul_hi_i32 v4, v3, s12
	v_lshrrev_b32_e32 v5, 31, v4
	v_ashrrev_i32_e32 v4, 3, v4
	v_add_u32_e32 v8, v4, v5
	s_movk_i32 s12, 0xff7f
	v_mul_lo_u32 v6, v8, s12
	v_add_u32_e32 v4, s27, v8
	v_ashrrev_i32_e32 v5, 31, v4
	v_add_lshl_u32 v6, v3, v6, s21
	v_min_i32_e32 v6, 0x7ff, v6
	v_lshlrev_b64 v[4:5], 13, v[4:5]
	v_ashrrev_i32_e32 v7, 31, v6
	v_lshl_add_u64 v[4:5], s[82:83], 0, v[4:5]
	v_lshl_add_u64 v[4:5], v[6:7], 2, v[4:5]
	global_load_dword v6, v[4:5], off
	s_movk_i32 s12, 0xff01
	v_add_u32_e32 v7, 0x200, v3
	v_cmp_lt_i32_e32 vcc, s12, v3
	s_movk_i32 s12, 0x1dfc
	s_or_b64 s[10:11], vcc, s[10:11]
	v_mad_u64_u32 v[4:5], s[12:13], v8, s12, v[0:1]
	v_add_u32_e32 v0, 0x800, v0
	v_mov_b32_e32 v3, v7
	s_waitcnt vmcnt(0) lgkmcnt(0)
	ds_write_b32 v4, v6
	s_andn2_b64 exec, exec, s[10:11]
	s_cbranch_execnz .LBB0_429
.LBB0_430:
	s_or_b64 exec, exec, s[0:1]
	s_ashr_i32 s0, s26, 8
	s_ashr_i32 s1, s26, 31
	s_xor_b32 s16, s1, s22
	s_abs_i32 s1, s0
	s_mul_hi_u32 s10, s1, s24
	s_mul_i32 s11, s10, s23
	s_sub_i32 s1, s1, s11
	s_add_i32 s11, s10, 1
	s_sub_i32 s12, s1, s23
	s_cmp_ge_u32 s1, s23
	s_cselect_b32 s10, s11, s10
	s_cselect_b32 s1, s12, s1
	s_add_i32 s11, s10, 1
	s_cmp_ge_u32 s1, s23
	s_cselect_b32 s1, s11, s10
	s_xor_b32 s17, s1, s16
	s_sub_i32 s11, s17, s16
	s_mul_i32 s1, s11, s3
	s_sub_i32 s0, s0, s1
	s_lshl_b32 s1, s26, 8
	s_ashr_i32 s10, s14, 8
	s_and_b32 s31, s1, 0xf800
	s_ashr_i32 s1, s0, 31
	s_add_u32 s12, s0, s31
	s_addc_u32 s13, s1, 0
	s_lshr_b32 s14, s14, 1
	s_lshl_b32 s15, s11, 7
	s_and_b32 s18, s14, 0x60
	v_and_b32_e32 v34, 31, v2
	s_or_b32 s28, s18, s15
	v_or_b32_e32 v4, s28, v34
	v_ashrrev_i32_e32 v5, 31, v4
	v_lshlrev_b64 v[4:5], s21, v[4:5]
	v_lshl_add_u64 v[4:5], v[4:5], 0, s[12:13]
	s_lshl_b32 s34, s25, 7
	s_lshl_b32 s19, s10, 6
	v_lshlrev_b64 v[6:7], 12, v[4:5]
	s_add_i32 s14, s19, s34
	v_bfe_u32 v178, v2, 5, 1
	v_lshl_add_u64 v[6:7], s[40:41], 0, v[6:7]
	s_ashr_i32 s15, s14, 31
	v_lshl_add_u64 v[6:7], s[14:15], 1, v[6:7]
	v_lshlrev_b32_e32 v120, 4, v178
	v_mov_b32_e32 v121, v1
	s_lshl_b32 s29, s11, 1
	v_ashrrev_i32_e32 v0, 3, v2
	s_lshl_b64 s[0:1], s[0:1], s20
	v_lshl_add_u64 v[6:7], v[6:7], 0, v[120:121]
	s_add_i32 s14, s29, -2
	v_ashrrev_i32_e32 v121, 4, v2
	v_lshlrev_b32_e32 v8, 4, v2
	v_add_u32_e32 v2, s34, v0
	s_cmp_gt_i32 s11, 0
	v_ashrrev_i32_e32 v3, 31, v2
	s_cselect_b32 s30, s14, 0
	s_lshl_b32 s11, s25, 8
	v_lshlrev_b64 v[2:3], 17, v[2:3]
	s_add_u32 s14, s61, s11
	v_lshl_add_u64 v[2:3], s[64:65], 0, v[2:3]
	s_addc_u32 s15, s2, 0
	v_and_b32_e32 v122, 0xf0, v8
	v_mov_b32_e32 v123, v1
	v_lshl_add_u64 v[2:3], s[0:1], 1, v[2:3]
	s_lshl_b32 s80, s31, 1
	v_lshl_add_u64 v[124:125], s[14:15], 0, v[122:123]
	v_lshl_add_u64 v[2:3], v[2:3], 0, s[80:81]
	v_and_b32_e32 v126, 0x70, v8
	v_mov_b32_e32 v127, v1
	s_lshl_b32 s14, s30, 6
	v_lshl_add_u64 v[128:129], v[2:3], 0, v[126:127]
	v_add_u32_e32 v2, s14, v121
	v_ashrrev_i32_e32 v3, 31, v2
	v_lshlrev_b64 v[8:9], s21, v[2:3]
	v_add_u32_e32 v2, 32, v2
	v_ashrrev_i32_e32 v3, 31, v2
	v_lshl_add_u64 v[8:9], v[8:9], 0, s[12:13]
	v_lshlrev_b64 v[2:3], s21, v[2:3]
	v_lshlrev_b64 v[8:9], 12, v[8:9]
	v_lshl_add_u64 v[2:3], v[2:3], 0, s[12:13]
	v_lshl_add_u64 v[8:9], v[124:125], 0, v[8:9]
	v_lshlrev_b64 v[2:3], 12, v[2:3]
	v_lshl_add_u64 v[2:3], v[124:125], 0, v[2:3]
	global_load_dwordx4 v[82:85], v[8:9], off
	global_load_dwordx4 v[86:89], v[2:3], off
	s_ashr_i32 s15, s14, 31
	s_lshl_b64 s[0:1], s[14:15], 1
	s_mov_b64 s[34:35], 0x800000
	v_lshl_add_u64 v[2:3], v[128:129], 0, s[0:1]
	v_lshl_add_u64 v[130:131], v[128:129], 0, s[34:35]
	v_lshl_add_u64 v[8:9], v[130:131], 0, s[0:1]
	global_load_dwordx4 v[90:93], v[2:3], off
	global_load_dwordx4 v[94:97], v[8:9], off
	global_load_dwordx4 v[66:69], v[6:7], off
	global_load_dwordx4 v[70:73], v[6:7], off offset:32
	global_load_dwordx4 v[74:77], v[6:7], off offset:64
	global_load_dwordx4 v[78:81], v[6:7], off offset:96
	v_cndmask_b32_e64 v2, 0, 1, s[4:5]
	v_mul_lo_u32 v127, v0, s51
	v_cmp_ne_u32_e64 s[0:1], 1, v2
	v_add3_u32 v2, 0, v127, v126
	v_mul_lo_u32 v123, v121, s50
	v_add_u32_e32 v6, 0x4400, v2
	v_add_u32_e32 v7, 0x6600, v2
	v_lshlrev_b64 v[2:3], 6, v[4:5]
	v_lshlrev_b64 v[4:5], 11, v[4:5]
	v_mov_b32_e32 v17, 0
	v_lshlrev_b32_e32 v112, 3, v178
	v_add3_u32 v0, 0, v123, v122
	s_andn2_b64 vcc, exec, s[4:5]
	v_lshl_add_u64 v[98:99], s[56:57], 0, v[2:3]
	v_lshl_add_u64 v[116:117], s[76:77], 0, v[4:5]
	v_mov_b32_e32 v113, 0
	s_waitcnt vmcnt(0)
	ds_write_b128 v0, v[82:85]
	ds_write_b128 v0, v[86:89] offset:8704
	ds_write2_b64 v6, v[90:91], v[92:93] offset1:1
	ds_write2_b64 v7, v[94:95], v[96:97] offset1:1
	s_cbranch_vccnz .LBB0_432
	s_lshl_b32 s80, s27, 2
	s_ashr_i32 s11, s10, 31
	v_lshl_add_u64 v[2:3], v[98:99], 0, s[80:81]
	v_lshl_add_u64 v[2:3], s[10:11], 2, v[2:3]
	s_add_i32 s11, s10, s27
	s_lshl_b32 s34, s11, 6
	s_ashr_i32 s35, s34, 31
	v_lshl_add_u64 v[4:5], s[34:35], 1, v[116:117]
	v_mov_b32_e32 v113, v1
	v_lshl_add_u64 v[4:5], v[4:5], 0, v[112:113]
	global_load_dword v113, v[2:3], off
	global_load_dwordx2 v[118:119], v[4:5], off
	global_load_dwordx2 v[114:115], v[4:5], off offset:16
	global_load_dwordx2 v[110:111], v[4:5], off offset:32
	global_load_dwordx2 v[108:109], v[4:5], off offset:48
	global_load_dwordx2 v[106:107], v[4:5], off offset:64
	global_load_dwordx2 v[104:105], v[4:5], off offset:80
	global_load_dwordx2 v[102:103], v[4:5], off offset:96
	global_load_dwordx2 v[100:101], v[4:5], off offset:112

; __device__ __forceinline__ unsigned cvt_pk_bf16(float lo, float hi) { f32x2_t v = {lo, hi}; bf16x2_t b = __builtin_convertvector(v, bf16x2_t); return __builtin_bit_cast(unsigned, b); }
; __device__ __forceinline__ float bflo(unsigned w) { return __uint_as_float(w << 16); }
; __device__ __forceinline__ float bfhi(unsigned w) { return __uint_as_float(w & 0xffff0000u); }
; template <int MODE> ...
;     ...
;             for (int g4 = 0; g4 < 4; ++g4) { const int dv0 = 32 * dvb + 8 * g4 + 4 * hi;
;                 float o0 = acc[dvb][4 * g4 + 0] * sc, o1 = acc[dvb][4 * g4 + 1] * sc, o2 = acc[dvb][4 * g4 + 2] * sc, o3 = acc[dvb][4 * g4 + 3] * sc;
;                 if (gidx > 0) { const u32x2 pw = pw_pre[dvb][g4]; o0 += wa * bflo(pw.x); o1 += wa * bfhi(pw.x); o2 += wa * bflo(pw.y); o3 += wa * bfhi(pw.y); }
;                 u32x2 w; w.x = cvt_pk_bf16(o0, o1); w.y = cvt_pk_bf16(o2, o3);
;                 *(u32x2*)(orow + dv0) = w; }
;         if (hi == 0 && gidx < 2) LSE[qtok * 16 + head] = lsen;
.LBB0_464:
	v_cmp_eq_u32_e32 vcc, 0, v178
	v_cvt_pk_bf16_f32 v248, v2, v3
	v_cvt_pk_bf16_f32 v249, v4, v5
	s_and_b64 s[12:13], s[8:9], vcc
	s_nop 1
	v_permlane32_swap_b32_e32 v246, v248
	v_permlane32_swap_b32_e32 v247, v249
	global_store_dwordx4 v[18:19], v[246:249], off offset:96
	s_and_saveexec_b64 s[0:1], s[12:13]
	s_cbranch_execz .LBB0_426
	s_ashr_i32 s11, s10, 31
	v_lshl_add_u64 v[2:3], s[10:11], 2, v[98:99]
	global_store_dword v[2:3], v36, off
	s_branch .LBB0_426
